# static s_setprio 1 for waves 4-7 over the P4/P5 attention+hyena item loops (cleared at loop exit)
# baseline (speedup 1.0000x reference)
.LBB0_611:
	v_readlane_b32 s0, v255, 14
	v_readlane_b32 s1, v255, 15
	s_and_b64 s[0:1], s[0:1], exec
	s_movk_i32 s0, 0x500
	s_cselect_b32 s74, s0, 0x400
	s_movk_i32 s0, 0x400
	s_cselect_b32 s64, 0x480, s0
	s_or_b32 s5, s64, 0x100
	s_add_i32 s22, s5, s74
	v_readfirstlane_b32 s0, v211
	s_nop 3
	s_lshr_b32 s0, s0, 8
	s_cmp_lg_u32 s0, 0
	s_cbranch_scc0 .Lprio4_done
	s_setprio 1
.Lprio4_done:
	s_cmp_ge_i32 s54, s22
	s_mul_i32 s16, s6, 0x900
	s_mul_i32 s14, s6, 0x300
	s_cbranch_scc1 .LBB0_790
	v_readlane_b32 s0, v255, 14
	v_readlane_b32 s76, v252, 0
	v_readlane_b32 s1, v255, 15
	v_readlane_b32 s77, v252, 1
	v_readlane_b32 s78, v252, 2
	v_readlane_b32 s79, v252, 3
	v_readlane_b32 s80, v252, 4
	v_readlane_b32 s81, v252, 5
	v_readlane_b32 s82, v252, 6
	v_readlane_b32 s83, v252, 7
	v_readlane_b32 s84, v252, 8
	v_readlane_b32 s85, v252, 9
	v_readlane_b32 s86, v252, 10
	v_readlane_b32 s87, v252, 11
	v_readlane_b32 s88, v252, 12
	v_readlane_b32 s89, v252, 13
	v_readlane_b32 s90, v252, 14
	v_readlane_b32 s91, v252, 15
	s_and_b64 s[0:1], s[0:1], exec
	s_mov_b32 s13, s77
	s_mov_b32 s17, s77
	v_readlane_b32 s76, v252, 44
	s_movk_i32 s0, 0xfa80
	v_readlane_b32 s78, v252, 46
	v_readlane_b32 s79, v252, 47
	s_cselect_b32 s23, s0, 0xfffffb00
	s_lshl_b64 s[0:1], s[16:17], 2
	s_mov_b64 s[6:7], s[78:79]
	v_readlane_b32 s80, v252, 48
	v_readlane_b32 s81, v252, 49
	s_add_u32 s17, s6, s0
	s_mov_b32 s15, s13
	s_mov_b64 s[8:9], s[80:81]
	s_addc_u32 s28, s7, s1
	s_lshl_b64 s[0:1], s[14:15], 2
	v_readlane_b32 s90, v252, 58
	v_readlane_b32 s91, v252, 59
	s_add_u32 s15, s8, s0
	v_readlane_b32 s6, v255, 10
	v_readlane_b32 s90, v254, 49
	v_readlane_b32 s80, v254, 55
	v_readlane_b32 s78, v254, 53
	s_addc_u32 s29, s9, s1
	s_lshl_b32 s0, s6, 10
	v_readlane_b32 s91, v254, 50
	v_readlane_b32 s81, v254, 56
	v_readlane_b32 s79, v254, 54
	s_lshl_b32 s34, s6, 9
	s_or_b32 s52, s0, 0x200
	s_lshl_b32 s75, s6, 3
	s_mov_b32 s35, s54
	v_readlane_b32 s77, v252, 45
	v_readlane_b32 s82, v252, 50
	v_readlane_b32 s83, v252, 51
	v_readlane_b32 s84, v252, 52
	v_readlane_b32 s85, v252, 53
	v_readlane_b32 s86, v252, 54
	v_readlane_b32 s87, v252, 55
	v_readlane_b32 s88, v252, 56
	v_readlane_b32 s89, v252, 57
	v_readlane_b32 s7, v255, 11
	s_branch .LBB0_615

.LBB0_790:
	s_setprio 0
	s_getreg_b32 s5, hwreg(HW_REG_XCC_ID, 0, 4)
	s_waitcnt vmcnt(0)
	s_waitcnt lgkmcnt(0)
	s_barrier
	s_mov_b64 s[0:1], exec
	v_readlane_b32 s6, v252, 16
	v_readlane_b32 s7, v252, 17
	v_readlane_b32 s18, v254, 51
	s_and_b64 s[6:7], s[0:1], s[6:7]
	v_readlane_b32 s19, v254, 52
	s_mov_b64 exec, s[6:7]
	s_cbranch_execz .LBB0_842
	v_readlane_b32 s4, v254, 35
	s_waitcnt vmcnt(0) expcnt(0) lgkmcnt(0)
	s_and_b32 s5, s5, 15
	v_mov_b32_e32 v0, s4
	ds_read_b32 v3, v0
	v_readlane_b32 s4, v254, 36
	s_waitcnt lgkmcnt(0)
	v_cmp_ne_u32_e32 vcc, 0, v3
	v_mov_b32_e32 v0, s4
	ds_read_b32 v2, v0
	s_cbranch_vccnz .LBB0_806
	s_mov_b32 s12, 1
	s_branch .LBB0_794

.LBB0_842:
	s_or_b64 exec, exec, s[0:1]
	s_lshl_b32 s25, s64, 1
	s_add_i32 s20, s25, s74
	v_readfirstlane_b32 s0, v211
	s_nop 3
	s_lshr_b32 s0, s0, 8
	s_cmp_lg_u32 s0, 0
	s_cbranch_scc0 .Lprio5_done
	s_setprio 1
.Lprio5_done:
	v_readlane_b32 s74, v254, 59
	s_cmp_ge_i32 s54, s20
	v_readlane_b32 s75, v254, 60
	s_waitcnt lgkmcnt(0)
	s_barrier
	s_cbranch_scc1 .LBB0_954
	v_readlane_b32 s76, v252, 0
	v_readlane_b32 s77, v252, 1
	v_readlane_b32 s78, v252, 2
	v_readlane_b32 s79, v252, 3
	v_readlane_b32 s80, v252, 4
	v_readlane_b32 s81, v252, 5
	v_readlane_b32 s82, v252, 6
	v_readlane_b32 s83, v252, 7
	v_readlane_b32 s84, v252, 8
	v_readlane_b32 s85, v252, 9
	v_readlane_b32 s86, v252, 10
	v_readlane_b32 s87, v252, 11
	v_readlane_b32 s88, v252, 12
	v_readlane_b32 s89, v252, 13
	v_readlane_b32 s90, v252, 14
	v_readlane_b32 s91, v252, 15
	s_mov_b32 s5, s77
	s_mov_b32 s17, s77
	v_readlane_b32 s76, v252, 44
	v_readlane_b32 s78, v252, 46
	v_readlane_b32 s79, v252, 47
	s_lshl_b64 s[0:1], s[16:17], 2
	s_mov_b64 s[6:7], s[78:79]
	v_readlane_b32 s80, v252, 48
	v_readlane_b32 s81, v252, 49
	s_add_u32 s21, s6, s0
	s_mov_b32 s15, s5
	s_mov_b64 s[8:9], s[80:81]
	s_addc_u32 s22, s7, s1
	s_lshl_b64 s[0:1], s[14:15], 2
	s_add_u32 s23, s8, s0
	v_readlane_b32 s88, v252, 56
	s_addc_u32 s28, s9, s1
	v_readlane_b32 s0, v255, 10
	v_readlane_b32 s84, v252, 52
	v_readlane_b32 s85, v252, 53
	v_readlane_b32 s86, v252, 54
	v_readlane_b32 s87, v252, 55
	v_readlane_b32 s89, v252, 57
	v_readlane_b32 s90, v252, 58
	v_readlane_b32 s91, v252, 59
	v_readlane_b32 s80, v254, 55
	v_readlane_b32 s78, v254, 53
	s_lshl_b32 s29, s0, 9
	s_lshl_b32 s88, s0, 10
	s_mov_b32 s91, 0xd000
	s_movk_i32 s87, 0x5000
	s_mov_b32 s86, 0x30000
	s_mov_b32 s85, 0x9000
	s_mov_b32 s84, 0xc000
	s_movk_i32 s65, 0x4000
	s_mov_b32 s52, 0x20000
	v_readlane_b32 s81, v254, 56
	v_readlane_b32 s79, v254, 54
	s_or_b32 s34, s29, 0x100
	s_or_b32 s35, s88, 0x300
	s_bitset1_b32 s88, 8
	s_lshl_b32 s89, s0, 3
	s_mov_b32 s90, s54
	v_readlane_b32 s77, v252, 45
	v_readlane_b32 s82, v252, 50
	v_readlane_b32 s83, v252, 51
	v_readlane_b32 s1, v255, 11
	s_branch .LBB0_847

.LBB0_954:
	s_setprio 0
	s_getreg_b32 s4, hwreg(HW_REG_XCC_ID, 0, 4)
	s_waitcnt vmcnt(0)
	s_barrier
	s_mov_b64 s[0:1], exec
	v_readlane_b32 s6, v252, 16
	v_readlane_b32 s7, v252, 17
	v_readlane_b32 s88, v255, 5
	v_readlane_b32 s90, v254, 49
	v_readlane_b32 s22, v254, 51
	s_and_b64 s[6:7], s[0:1], s[6:7]
	v_readlane_b32 s89, v255, 6
	v_readlane_b32 s91, v254, 50
	v_readlane_b32 s23, v254, 52
	s_mov_b64 exec, s[6:7]
	s_cbranch_execz .LBB0_1006
	v_readlane_b32 s5, v254, 35
	s_waitcnt vmcnt(0) expcnt(0) lgkmcnt(0)
	s_and_b32 s4, s4, 15
	v_mov_b32_e32 v0, s5
	ds_read_b32 v3, v0
	v_readlane_b32 s5, v254, 36
	s_waitcnt lgkmcnt(0)
	v_cmp_ne_u32_e32 vcc, 0, v3
	v_mov_b32_e32 v0, s5
	ds_read_b32 v2, v0
	s_cbranch_vccnz .LBB0_970
	s_mov_b32 s5, 1
	s_branch .LBB0_958
